# G1 epilogue stores transposed through a per-wave LDS slot so each store covers 4 rows x 64 B per 16 lanes
# speedup vs baseline: 1.0110x; 1.0030x over previous
.LBB0_132:
	s_add_u32 s2, s6, 0xfffc0080
	s_addc_u32 s3, s7, -1
	s_add_i32 s23, 0, 0x10000
	v_add_u32_e32 v150, s23, v157
	ds_read_b128 v[138:141], v150
	ds_read_b128 v[142:145], v150 offset:1024
	ds_read_b128 v[146:149], v150 offset:2048
	ds_read_b128 v[150:153], v150 offset:3072
	s_cmp_eq_u32 s22, 12
	s_cselect_b32 s21, s15, s3
	s_cselect_b32 s20, s37, s2
	s_cselect_b32 s3, s13, s40
	s_cselect_b32 s2, s38, s39
	v_lshl_add_u64 v[154:155], s[6:7], 0, v[136:137]
	s_add_i32 m0, s26, 0xc000
	ds_read_b128 v[160:163], v159
	ds_read_b128 v[164:167], v159 offset:1024
	ds_read_b128 v[168:171], v159 offset:2048
	ds_read_b128 v[172:175], v159 offset:3072
	ds_read_b128 v[176:179], v159 offset:4096
	ds_read_b128 v[180:183], v159 offset:5120
	ds_read_b128 v[184:187], v159 offset:6144
	ds_read_b128 v[188:191], v159 offset:7168
	global_load_lds_dwordx4 v[154:155], off
	v_lshl_add_u64 v[154:155], s[6:7], 0, v[134:135]
	s_add_i32 m0, s26, 0xe000
	s_nop 0
	global_load_lds_dwordx4 v[154:155], off
	s_waitcnt lgkmcnt(8)
	s_barrier
	s_waitcnt lgkmcnt(0)
	s_setprio 1
	s_waitcnt lgkmcnt(0)
	v_mfma_f32_16x16x32_bf16 v[112:115], v[138:141], v[160:163], v[112:115]
	v_mfma_f32_16x16x32_bf16 v[116:119], v[146:149], v[160:163], v[116:119]
	v_mfma_f32_16x16x32_bf16 v[96:99], v[138:141], v[168:171], v[96:99]
	v_mfma_f32_16x16x32_bf16 v[100:103], v[146:149], v[168:171], v[100:103]
	v_mfma_f32_16x16x32_bf16 v[80:83], v[138:141], v[176:179], v[80:83]
	v_mfma_f32_16x16x32_bf16 v[84:87], v[146:149], v[176:179], v[84:87]
	v_mfma_f32_16x16x32_bf16 v[48:51], v[138:141], v[184:187], v[48:51]
	v_mfma_f32_16x16x32_bf16 v[56:59], v[146:149], v[184:187], v[56:59]
	v_mfma_f32_16x16x32_bf16 v[112:115], v[142:145], v[164:167], v[112:115]
	v_mfma_f32_16x16x32_bf16 v[116:119], v[150:153], v[164:167], v[116:119]
	v_mfma_f32_16x16x32_bf16 v[96:99], v[142:145], v[172:175], v[96:99]
	v_mfma_f32_16x16x32_bf16 v[100:103], v[150:153], v[172:175], v[100:103]
	v_mfma_f32_16x16x32_bf16 v[80:83], v[142:145], v[180:183], v[80:83]
	v_mfma_f32_16x16x32_bf16 v[84:87], v[150:153], v[180:183], v[84:87]
	v_mfma_f32_16x16x32_bf16 v[48:51], v[142:145], v[188:191], v[48:51]
	v_mfma_f32_16x16x32_bf16 v[56:59], v[150:153], v[188:191], v[56:59]
	s_setprio 0
	s_barrier
	s_add_i32 s41, 0, 0x14000
	v_add_u32_e32 v154, s41, v157
	s_add_i32 s23, s23, s25
	ds_read_b128 v[206:209], v154
	ds_read_b128 v[210:213], v154 offset:1024
	ds_read_b128 v[214:217], v154 offset:2048
	ds_read_b128 v[218:221], v154 offset:3072
	v_lshl_add_u64 v[154:155], s[2:3], 0, v[194:195]
	s_mov_b32 m0, s23
	v_lshl_add_u64 v[222:223], s[2:3], 0, v[128:129]
	global_load_lds_dwordx4 v[154:155], off
	s_add_i32 m0, s23, 0x2000
	s_nop 0
	global_load_lds_dwordx4 v[222:223], off
	s_barrier
	s_waitcnt lgkmcnt(0)
	s_setprio 1
	s_waitcnt lgkmcnt(0)
	v_mfma_f32_16x16x32_bf16 v[120:123], v[206:209], v[160:163], v[120:123]
	v_mfma_f32_16x16x32_bf16 v[124:127], v[214:217], v[160:163], v[124:127]
	v_mfma_f32_16x16x32_bf16 v[104:107], v[206:209], v[168:171], v[104:107]
	v_mfma_f32_16x16x32_bf16 v[108:111], v[214:217], v[168:171], v[108:111]
	v_mfma_f32_16x16x32_bf16 v[88:91], v[206:209], v[176:179], v[88:91]
	v_mfma_f32_16x16x32_bf16 v[92:95], v[214:217], v[176:179], v[92:95]
	v_mfma_f32_16x16x32_bf16 v[64:67], v[206:209], v[184:187], v[64:67]
	v_mfma_f32_16x16x32_bf16 v[72:75], v[214:217], v[184:187], v[72:75]
	v_mfma_f32_16x16x32_bf16 v[120:123], v[210:213], v[164:167], v[120:123]
	v_mfma_f32_16x16x32_bf16 v[124:127], v[218:221], v[164:167], v[124:127]
	v_mfma_f32_16x16x32_bf16 v[104:107], v[210:213], v[172:175], v[104:107]
	v_mfma_f32_16x16x32_bf16 v[108:111], v[218:221], v[172:175], v[108:111]
	v_mfma_f32_16x16x32_bf16 v[88:91], v[210:213], v[180:183], v[88:91]
	v_mfma_f32_16x16x32_bf16 v[92:95], v[218:221], v[180:183], v[92:95]
	v_mfma_f32_16x16x32_bf16 v[64:67], v[210:213], v[188:191], v[64:67]
	v_mfma_f32_16x16x32_bf16 v[72:75], v[218:221], v[188:191], v[72:75]
	s_setprio 0
	s_mov_b32 m0, s26
	v_lshl_add_u64 v[224:225], s[20:21], 0, v[132:133]
	s_barrier
	ds_read_b128 v[160:163], v159 offset:16384
	ds_read_b128 v[164:167], v159 offset:17408
	ds_read_b128 v[168:171], v159 offset:18432
	ds_read_b128 v[172:175], v159 offset:19456
	ds_read_b128 v[176:179], v159 offset:20480
	ds_read_b128 v[180:183], v159 offset:21504
	ds_read_b128 v[184:187], v159 offset:22528
	ds_read_b128 v[188:191], v159 offset:23552
	global_load_lds_dwordx4 v[224:225], off
	v_lshl_add_u64 v[226:227], s[20:21], 0, v[130:131]
	s_mov_b32 m0, s27
	s_nop 0
	global_load_lds_dwordx4 v[226:227], off
	s_barrier
	s_waitcnt lgkmcnt(0)
	s_setprio 1
	s_waitcnt lgkmcnt(0)
	v_mfma_f32_16x16x32_bf16 v[52:55], v[138:141], v[160:163], v[52:55]
	v_mfma_f32_16x16x32_bf16 v[60:63], v[146:149], v[160:163], v[60:63]
	v_mfma_f32_16x16x32_bf16 v[32:35], v[138:141], v[168:171], v[32:35]
	v_mfma_f32_16x16x32_bf16 v[36:39], v[146:149], v[168:171], v[36:39]
	v_mfma_f32_16x16x32_bf16 v[16:19], v[138:141], v[176:179], v[16:19]
	v_mfma_f32_16x16x32_bf16 v[20:23], v[146:149], v[176:179], v[20:23]
	v_mfma_f32_16x16x32_bf16 v[0:3], v[138:141], v[184:187], v[0:3]
	v_mfma_f32_16x16x32_bf16 v[4:7], v[146:149], v[184:187], v[4:7]
	v_mfma_f32_16x16x32_bf16 v[52:55], v[142:145], v[164:167], v[52:55]
	v_mfma_f32_16x16x32_bf16 v[60:63], v[150:153], v[164:167], v[60:63]
	v_mfma_f32_16x16x32_bf16 v[32:35], v[142:145], v[172:175], v[32:35]
	v_mfma_f32_16x16x32_bf16 v[36:39], v[150:153], v[172:175], v[36:39]
	v_mfma_f32_16x16x32_bf16 v[16:19], v[142:145], v[180:183], v[16:19]
	v_mfma_f32_16x16x32_bf16 v[20:23], v[150:153], v[180:183], v[20:23]
	v_mfma_f32_16x16x32_bf16 v[0:3], v[142:145], v[188:191], v[0:3]
	v_mfma_f32_16x16x32_bf16 v[4:7], v[150:153], v[188:191], v[4:7]
	s_setprio 0
	s_barrier
	s_add_u32 s56, s2, 0x40000
	s_addc_u32 s57, s3, 0
	s_add_i32 s23, s41, s25
	v_lshl_add_u64 v[138:139], s[56:57], 0, v[194:195]
	s_mov_b32 m0, s23
	s_nop 0
	global_load_lds_dwordx4 v[138:139], off
	v_lshl_add_u64 v[138:139], s[56:57], 0, v[128:129]
	s_add_i32 m0, s23, 0x2000
	s_nop 0
	global_load_lds_dwordx4 v[138:139], off
	s_waitcnt vmcnt(6)
	s_barrier
	s_setprio 1
	v_mfma_f32_16x16x32_bf16 v[68:71], v[206:209], v[160:163], v[68:71]
	v_mfma_f32_16x16x32_bf16 v[76:79], v[214:217], v[160:163], v[76:79]
	v_mfma_f32_16x16x32_bf16 v[40:43], v[206:209], v[168:171], v[40:43]
	v_mfma_f32_16x16x32_bf16 v[44:47], v[214:217], v[168:171], v[44:47]
	v_mfma_f32_16x16x32_bf16 v[24:27], v[206:209], v[176:179], v[24:27]
	v_mfma_f32_16x16x32_bf16 v[28:31], v[214:217], v[176:179], v[28:31]
	v_mfma_f32_16x16x32_bf16 v[8:11], v[206:209], v[184:187], v[8:11]
	v_mfma_f32_16x16x32_bf16 v[12:15], v[214:217], v[184:187], v[12:15]
	v_mfma_f32_16x16x32_bf16 v[68:71], v[210:213], v[164:167], v[68:71]
	v_mfma_f32_16x16x32_bf16 v[76:79], v[218:221], v[164:167], v[76:79]
	v_mfma_f32_16x16x32_bf16 v[40:43], v[210:213], v[172:175], v[40:43]
	v_mfma_f32_16x16x32_bf16 v[44:47], v[218:221], v[172:175], v[44:47]
	v_mfma_f32_16x16x32_bf16 v[24:27], v[210:213], v[180:183], v[24:27]
	v_mfma_f32_16x16x32_bf16 v[28:31], v[218:221], v[180:183], v[28:31]
	v_mfma_f32_16x16x32_bf16 v[8:11], v[210:213], v[188:191], v[8:11]
	v_mfma_f32_16x16x32_bf16 v[12:15], v[218:221], v[188:191], v[12:15]
	s_setprio 0
	s_add_i32 s23, 0, 0x18000
	v_add_u32_e32 v150, s23, v157
	s_barrier
	ds_read_b128 v[138:141], v150
	ds_read_b128 v[142:145], v150 offset:1024
	ds_read_b128 v[146:149], v150 offset:2048
	ds_read_b128 v[150:153], v150 offset:3072
	s_add_u32 s20, s20, 0x40000
	s_addc_u32 s21, s21, 0
	s_mov_b32 m0, s28
	v_lshl_add_u64 v[206:207], s[20:21], 0, v[132:133]
	ds_read_b128 v[160:163], v159 offset:32768
	ds_read_b128 v[164:167], v159 offset:33792
	ds_read_b128 v[168:171], v159 offset:34816
	ds_read_b128 v[172:175], v159 offset:35840
	ds_read_b128 v[176:179], v159 offset:36864
	ds_read_b128 v[180:183], v159 offset:37888
	ds_read_b128 v[184:187], v159 offset:38912
	ds_read_b128 v[188:191], v159 offset:39936
	global_load_lds_dwordx4 v[206:207], off
	v_lshl_add_u64 v[206:207], s[20:21], 0, v[130:131]
	s_mov_b32 m0, s29
	s_nop 0
	global_load_lds_dwordx4 v[206:207], off
	s_waitcnt lgkmcnt(8)
	s_barrier
	s_waitcnt lgkmcnt(0)
	s_setprio 1
	s_waitcnt lgkmcnt(0)
	v_mfma_f32_16x16x32_bf16 v[112:115], v[138:141], v[160:163], v[112:115]
	v_mfma_f32_16x16x32_bf16 v[116:119], v[146:149], v[160:163], v[116:119]
	v_mfma_f32_16x16x32_bf16 v[96:99], v[138:141], v[168:171], v[96:99]
	v_mfma_f32_16x16x32_bf16 v[100:103], v[146:149], v[168:171], v[100:103]
	v_mfma_f32_16x16x32_bf16 v[80:83], v[138:141], v[176:179], v[80:83]
	v_mfma_f32_16x16x32_bf16 v[84:87], v[146:149], v[176:179], v[84:87]
	v_mfma_f32_16x16x32_bf16 v[48:51], v[138:141], v[184:187], v[48:51]
	v_mfma_f32_16x16x32_bf16 v[56:59], v[146:149], v[184:187], v[56:59]
	v_mfma_f32_16x16x32_bf16 v[112:115], v[142:145], v[164:167], v[112:115]
	v_mfma_f32_16x16x32_bf16 v[116:119], v[150:153], v[164:167], v[116:119]
	v_mfma_f32_16x16x32_bf16 v[96:99], v[142:145], v[172:175], v[96:99]
	v_mfma_f32_16x16x32_bf16 v[100:103], v[150:153], v[172:175], v[100:103]
	v_mfma_f32_16x16x32_bf16 v[80:83], v[142:145], v[180:183], v[80:83]
	v_mfma_f32_16x16x32_bf16 v[84:87], v[150:153], v[180:183], v[84:87]
	v_mfma_f32_16x16x32_bf16 v[48:51], v[142:145], v[188:191], v[48:51]
	v_mfma_f32_16x16x32_bf16 v[56:59], v[150:153], v[188:191], v[56:59]
	s_setprio 0
	s_barrier
	s_add_i32 s20, 0, 0x1c000
	s_add_i32 s21, s23, s25
	v_add_u32_e32 v193, s20, v157
	v_lshl_add_u64 v[154:155], v[154:155], 0, s[70:71]
	s_mov_b32 m0, s21
	ds_read_b128 v[206:209], v193
	ds_read_b128 v[210:213], v193 offset:1024
	ds_read_b128 v[214:217], v193 offset:2048
	ds_read_b128 v[218:221], v193 offset:3072
	global_load_lds_dwordx4 v[154:155], off
	v_lshl_add_u64 v[154:155], v[222:223], 0, s[70:71]
	s_add_i32 m0, s21, 0x2000
	s_nop 0
	global_load_lds_dwordx4 v[154:155], off
	s_barrier
	s_waitcnt lgkmcnt(0)
	s_setprio 1
	s_waitcnt lgkmcnt(0)
	v_mfma_f32_16x16x32_bf16 v[120:123], v[206:209], v[160:163], v[120:123]
	v_mfma_f32_16x16x32_bf16 v[124:127], v[214:217], v[160:163], v[124:127]
	v_mfma_f32_16x16x32_bf16 v[104:107], v[206:209], v[168:171], v[104:107]
	v_mfma_f32_16x16x32_bf16 v[108:111], v[214:217], v[168:171], v[108:111]
	v_mfma_f32_16x16x32_bf16 v[88:91], v[206:209], v[176:179], v[88:91]
	v_mfma_f32_16x16x32_bf16 v[92:95], v[214:217], v[176:179], v[92:95]
	v_mfma_f32_16x16x32_bf16 v[64:67], v[206:209], v[184:187], v[64:67]
	v_mfma_f32_16x16x32_bf16 v[72:75], v[214:217], v[184:187], v[72:75]
	v_mfma_f32_16x16x32_bf16 v[120:123], v[210:213], v[164:167], v[120:123]
	v_mfma_f32_16x16x32_bf16 v[124:127], v[218:221], v[164:167], v[124:127]
	v_mfma_f32_16x16x32_bf16 v[104:107], v[210:213], v[172:175], v[104:107]
	v_mfma_f32_16x16x32_bf16 v[108:111], v[218:221], v[172:175], v[108:111]
	v_mfma_f32_16x16x32_bf16 v[88:91], v[210:213], v[180:183], v[88:91]
	v_mfma_f32_16x16x32_bf16 v[92:95], v[218:221], v[180:183], v[92:95]
	v_mfma_f32_16x16x32_bf16 v[64:67], v[210:213], v[188:191], v[64:67]
	v_mfma_f32_16x16x32_bf16 v[72:75], v[218:221], v[188:191], v[72:75]
	s_setprio 0
	s_mov_b32 m0, s30
	v_lshl_add_u64 v[154:155], v[224:225], 0, s[70:71]
	s_barrier
	ds_read_b128 v[160:163], v159 offset:49152
	ds_read_b128 v[164:167], v159 offset:50176
	ds_read_b128 v[168:171], v159 offset:51200
	ds_read_b128 v[172:175], v159 offset:52224
	ds_read_b128 v[176:179], v159 offset:53248
	ds_read_b128 v[180:183], v159 offset:54272
	ds_read_b128 v[184:187], v159 offset:55296
	ds_read_b128 v[188:191], v159 offset:56320
	global_load_lds_dwordx4 v[154:155], off
	v_lshl_add_u64 v[154:155], v[226:227], 0, s[70:71]
	s_mov_b32 m0, s31
	s_nop 0
	global_load_lds_dwordx4 v[154:155], off
	s_barrier
	s_waitcnt lgkmcnt(0)
	s_setprio 1
	s_waitcnt lgkmcnt(0)
	v_mfma_f32_16x16x32_bf16 v[52:55], v[138:141], v[160:163], v[52:55]
	v_mfma_f32_16x16x32_bf16 v[60:63], v[146:149], v[160:163], v[60:63]
	v_mfma_f32_16x16x32_bf16 v[32:35], v[138:141], v[168:171], v[32:35]
	v_mfma_f32_16x16x32_bf16 v[36:39], v[146:149], v[168:171], v[36:39]
	v_mfma_f32_16x16x32_bf16 v[16:19], v[138:141], v[176:179], v[16:19]
	v_mfma_f32_16x16x32_bf16 v[20:23], v[146:149], v[176:179], v[20:23]
	v_mfma_f32_16x16x32_bf16 v[0:3], v[138:141], v[184:187], v[0:3]
	v_mfma_f32_16x16x32_bf16 v[4:7], v[146:149], v[184:187], v[4:7]
	v_mfma_f32_16x16x32_bf16 v[52:55], v[142:145], v[164:167], v[52:55]
	v_mfma_f32_16x16x32_bf16 v[60:63], v[150:153], v[164:167], v[60:63]
	v_mfma_f32_16x16x32_bf16 v[32:35], v[142:145], v[172:175], v[32:35]
	v_mfma_f32_16x16x32_bf16 v[36:39], v[150:153], v[172:175], v[36:39]
	v_mfma_f32_16x16x32_bf16 v[16:19], v[142:145], v[180:183], v[16:19]
	v_mfma_f32_16x16x32_bf16 v[20:23], v[150:153], v[180:183], v[20:23]
	v_mfma_f32_16x16x32_bf16 v[0:3], v[142:145], v[188:191], v[0:3]
	v_mfma_f32_16x16x32_bf16 v[4:7], v[150:153], v[188:191], v[4:7]
	s_setprio 0
	s_barrier
	s_add_u32 s2, s2, 0x40080
	s_addc_u32 s3, s3, 0
	s_add_i32 s20, s20, s25
	v_lshl_add_u64 v[138:139], s[2:3], 0, v[194:195]
	s_mov_b32 m0, s20
	s_nop 0
	global_load_lds_dwordx4 v[138:139], off
	v_lshl_add_u64 v[138:139], s[2:3], 0, v[128:129]
	s_add_i32 m0, s20, 0x2000
	s_nop 0
	global_load_lds_dwordx4 v[138:139], off
	s_waitcnt vmcnt(6)
	s_barrier
	s_setprio 1
	v_mfma_f32_16x16x32_bf16 v[68:71], v[206:209], v[160:163], v[68:71]
	v_mfma_f32_16x16x32_bf16 v[76:79], v[214:217], v[160:163], v[76:79]
	v_mfma_f32_16x16x32_bf16 v[40:43], v[206:209], v[168:171], v[40:43]
	v_mfma_f32_16x16x32_bf16 v[44:47], v[214:217], v[168:171], v[44:47]
	v_mfma_f32_16x16x32_bf16 v[24:27], v[206:209], v[176:179], v[24:27]
	v_mfma_f32_16x16x32_bf16 v[28:31], v[214:217], v[176:179], v[28:31]
	v_mfma_f32_16x16x32_bf16 v[8:11], v[206:209], v[184:187], v[8:11]
	v_mfma_f32_16x16x32_bf16 v[12:15], v[214:217], v[184:187], v[12:15]
	v_mfma_f32_16x16x32_bf16 v[68:71], v[210:213], v[164:167], v[68:71]
	v_mfma_f32_16x16x32_bf16 v[76:79], v[218:221], v[164:167], v[76:79]
	v_mfma_f32_16x16x32_bf16 v[40:43], v[210:213], v[172:175], v[40:43]
	v_mfma_f32_16x16x32_bf16 v[44:47], v[218:221], v[172:175], v[44:47]
	v_mfma_f32_16x16x32_bf16 v[24:27], v[210:213], v[180:183], v[24:27]
	v_mfma_f32_16x16x32_bf16 v[28:31], v[218:221], v[180:183], v[28:31]
	v_mfma_f32_16x16x32_bf16 v[8:11], v[210:213], v[188:191], v[8:11]
	v_mfma_f32_16x16x32_bf16 v[12:15], v[218:221], v[188:191], v[12:15]
	s_setprio 0
	s_add_i32 s22, s22, 2
	s_add_u32 s39, s39, 0x100
	s_addc_u32 s40, s40, 0
	s_add_u32 s6, s6, 0x100
	s_addc_u32 s7, s7, 0
	s_cmp_gt_u32 s22, 13
	s_barrier
	s_cbranch_scc0 .LBB0_132
	v_lshl_add_u32 v140, s36, 8, v156
	v_ashrrev_i32_e32 v141, 31, v140
	v_lshl_add_u64 v[138:139], v[140:141], 3, s[10:11]
	global_load_dwordx2 v[142:143], v[138:139], off
	global_load_dwordx2 v[160:161], v[138:139], off offset:128
	global_load_dwordx2 v[154:155], v[138:139], off offset:256
	global_load_dwordx2 v[152:153], v[138:139], off offset:384
	s_mov_b32 s20, 0x800000
	global_load_dwordx2 v[150:151], v[138:139], off offset:1024
	global_load_dwordx2 v[148:149], v[138:139], off offset:1152
	global_load_dwordx2 v[146:147], v[138:139], off offset:1280
	s_nop 0
	global_load_dwordx2 v[138:139], v[138:139], off offset:1408
	v_lshl_or_b32 v144, s35, 8, v158
	v_ashrrev_i32_e32 v145, 31, v144
	v_lshlrev_b64 v[144:145], 1, v[144:145]
	v_add_u32_e32 v141, 0x80, v140
	v_readlane_b32 s38, v255, 9
	v_readlane_b32 s39, v255, 10
	s_waitcnt vmcnt(0) lgkmcnt(0)
	v_mbcnt_lo_u32_b32 v196, -1, 0
	v_mbcnt_hi_u32_b32 v196, -1, v196
	v_and_b32_e32 v198, 15, v196
	v_lshrrev_b32_e32 v199, 4, v196
	v_lshrrev_b32_e32 v202, 2, v198
	v_xor_b32_e32 v202, v202, v199
	v_lshlrev_b32_e32 v202, 4, v202
	v_lshl_or_b32 v202, v198, 6, v202
	s_lshl_b32 s100, s89, 11
	s_add_i32 s100, s100, 0x20000
	v_add_u32_e32 v202, s100, v202
	v_add_u32_e32 v203, 0x400, v202
	v_lshl_add_u32 v204, v196, 4, s100
	v_add_u32_e32 v205, 0x400, v204
	v_lshrrev_b32_e32 v250, 2, v196
	v_sub_u32_e32 v250, v250, v198
	v_mul_i32_i24_e32 v250, 0x1400, v250
	v_and_b32_e32 v251, 3, v196
	v_xor_b32_e32 v251, v251, v199
	v_sub_u32_e32 v251, v251, v199
	v_lshlrev_b32_e32 v251, 4, v251
	v_add_u32_e32 v250, v250, v251
	v_ashrrev_i32_e32 v251, 31, v250
	v_ffbh_u32_e32 v162, v143
	v_min_u32_e32 v162, 32, v162
	v_lshlrev_b64 v[142:143], v162, v[142:143]
	v_min_u32_e32 v142, 1, v142
	v_or_b32_e32 v142, v143, v142
	v_cvt_f32_u32_e32 v142, v142
	v_sub_u32_e32 v143, 32, v162
	v_ldexp_f32 v142, v142, v143
	v_fmamk_f32 v142, v142, 0x2e800000, v236
	v_cmp_gt_f32_e32 vcc, s20, v142
	v_mul_f32_e32 v143, 0x4b800000, v142
	s_nop 0
	v_cndmask_b32_e32 v142, v142, v143, vcc
	v_rsq_f32_e32 v142, v142
	s_nop 0
	v_mul_f32_e32 v143, 0x45800000, v142
	v_cndmask_b32_e32 v162, v142, v143, vcc
	v_mov_b64_e32 v[142:143], s[8:9]
	v_mad_i64_i32 v[164:165], s[2:3], v140, s86, v[142:143]
	v_pk_mul_f32 v[114:115], v[114:115], v[162:163] op_sel_hi:[1,0]
	v_pk_mul_f32 v[112:113], v[112:113], v[162:163] op_sel_hi:[1,0]
	v_pk_mul_f32 v[118:119], v[118:119], v[162:163] op_sel_hi:[1,0]
	v_pk_mul_f32 v[116:117], v[116:117], v[162:163] op_sel_hi:[1,0]
	v_lshl_add_u64 v[164:165], v[164:165], 0, v[144:145]
	v_cvt_pk_bf16_f32 v112, v112, v113
	v_cvt_pk_bf16_f32 v113, v114, v115
	v_cvt_pk_bf16_f32 v114, v116, v117
	v_cvt_pk_bf16_f32 v115, v118, v119
	ds_write_b128 v202, v[112:115]
	ds_read_b128 v[228:231], v204
	v_lshl_add_u64 v[246:247], v[164:165], 0, v[250:251]
	v_pk_mul_f32 v[116:117], v[126:127], v[162:163] op_sel_hi:[1,0]
	v_pk_mul_f32 v[118:119], v[124:125], v[162:163] op_sel_hi:[1,0]
	v_pk_mul_f32 v[114:115], v[122:123], v[162:163] op_sel_hi:[1,0]
	v_pk_mul_f32 v[112:113], v[120:121], v[162:163] op_sel_hi:[1,0]
	s_nop 0
	v_cvt_pk_bf16_f32 v112, v112, v113
	v_cvt_pk_bf16_f32 v113, v114, v115
	v_cvt_pk_bf16_f32 v114, v118, v119
	v_cvt_pk_bf16_f32 v115, v116, v117
	ds_write_b128 v203, v[112:115]
	ds_read_b128 v[232:235], v205
	v_lshl_add_u64 v[248:249], v[164:165], 0, v[250:251]
	s_waitcnt lgkmcnt(2)
	global_store_dwordx4 v[246:247], v[228:231], off
	s_nop 1
	v_ffbh_u32_e32 v112, v161
	v_min_u32_e32 v115, 32, v112
	v_lshlrev_b64 v[112:113], v115, v[160:161]
	v_min_u32_e32 v112, 1, v112
	v_or_b32_e32 v112, v113, v112
	v_cvt_f32_u32_e32 v112, v112
	v_sub_u32_e32 v113, 32, v115
	v_or_b32_e32 v114, 16, v140
	v_mad_i64_i32 v[114:115], s[2:3], v114, s86, v[142:143]
	v_ldexp_f32 v112, v112, v113
	v_fmamk_f32 v112, v112, 0x2e800000, v236
	v_cmp_gt_f32_e32 vcc, s20, v112
	v_mul_f32_e32 v113, 0x4b800000, v112
	v_lshl_add_u64 v[114:115], v[114:115], 0, v[144:145]
	v_cndmask_b32_e32 v112, v112, v113, vcc
	v_rsq_f32_e32 v112, v112
	s_nop 0
	v_mul_f32_e32 v113, 0x45800000, v112
	v_cndmask_b32_e32 v112, v112, v113, vcc
	v_pk_mul_f32 v[98:99], v[98:99], v[112:113] op_sel_hi:[1,0]
	v_pk_mul_f32 v[96:97], v[96:97], v[112:113] op_sel_hi:[1,0]
	v_pk_mul_f32 v[102:103], v[102:103], v[112:113] op_sel_hi:[1,0]
	v_pk_mul_f32 v[100:101], v[100:101], v[112:113] op_sel_hi:[1,0]
	v_cvt_pk_bf16_f32 v96, v96, v97
	v_cvt_pk_bf16_f32 v97, v98, v99
	v_cvt_pk_bf16_f32 v98, v100, v101
	v_cvt_pk_bf16_f32 v99, v102, v103
	ds_write_b128 v202, v[96:99]
	ds_read_b128 v[228:231], v204
	v_lshl_add_u64 v[246:247], v[114:115], 0, v[250:251]
	s_waitcnt lgkmcnt(2)
	global_store_dwordx4 v[248:249], v[232:235], off offset:256
	v_pk_mul_f32 v[100:101], v[110:111], v[112:113] op_sel_hi:[1,0]
	v_pk_mul_f32 v[102:103], v[108:109], v[112:113] op_sel_hi:[1,0]
	v_pk_mul_f32 v[98:99], v[106:107], v[112:113] op_sel_hi:[1,0]
	v_pk_mul_f32 v[96:97], v[104:105], v[112:113] op_sel_hi:[1,0]
	s_nop 0
	v_cvt_pk_bf16_f32 v96, v96, v97
	v_cvt_pk_bf16_f32 v97, v98, v99
	v_cvt_pk_bf16_f32 v98, v102, v103
	v_cvt_pk_bf16_f32 v99, v100, v101
	ds_write_b128 v203, v[96:99]
	ds_read_b128 v[232:235], v205
	v_lshl_add_u64 v[248:249], v[114:115], 0, v[250:251]
	s_waitcnt lgkmcnt(2)
	global_store_dwordx4 v[246:247], v[228:231], off
	s_nop 1
	v_ffbh_u32_e32 v96, v155
	v_min_u32_e32 v99, 32, v96
	v_lshlrev_b64 v[96:97], v99, v[154:155]
	v_min_u32_e32 v96, 1, v96
	v_or_b32_e32 v96, v97, v96
	v_cvt_f32_u32_e32 v96, v96
	v_sub_u32_e32 v97, 32, v99
	v_or_b32_e32 v98, 32, v140
	v_mad_i64_i32 v[98:99], s[2:3], v98, s86, v[142:143]
	v_ldexp_f32 v96, v96, v97
	v_fmamk_f32 v96, v96, 0x2e800000, v236
	v_cmp_gt_f32_e32 vcc, s20, v96
	v_mul_f32_e32 v97, 0x4b800000, v96
	v_lshl_add_u64 v[98:99], v[98:99], 0, v[144:145]
	v_cndmask_b32_e32 v96, v96, v97, vcc
	v_rsq_f32_e32 v96, v96
	s_nop 0
	v_mul_f32_e32 v97, 0x45800000, v96
	v_cndmask_b32_e32 v96, v96, v97, vcc
	v_pk_mul_f32 v[82:83], v[82:83], v[96:97] op_sel_hi:[1,0]
	v_pk_mul_f32 v[80:81], v[80:81], v[96:97] op_sel_hi:[1,0]
	v_pk_mul_f32 v[86:87], v[86:87], v[96:97] op_sel_hi:[1,0]
	v_pk_mul_f32 v[84:85], v[84:85], v[96:97] op_sel_hi:[1,0]
	v_cvt_pk_bf16_f32 v80, v80, v81
	v_cvt_pk_bf16_f32 v81, v82, v83
	v_cvt_pk_bf16_f32 v82, v84, v85
	v_cvt_pk_bf16_f32 v83, v86, v87
	ds_write_b128 v202, v[80:83]
	ds_read_b128 v[228:231], v204
	v_lshl_add_u64 v[246:247], v[98:99], 0, v[250:251]
	s_waitcnt lgkmcnt(2)
	global_store_dwordx4 v[248:249], v[232:235], off offset:256
	v_pk_mul_f32 v[84:85], v[94:95], v[96:97] op_sel_hi:[1,0]
	v_pk_mul_f32 v[86:87], v[92:93], v[96:97] op_sel_hi:[1,0]
	v_pk_mul_f32 v[82:83], v[90:91], v[96:97] op_sel_hi:[1,0]
	v_pk_mul_f32 v[80:81], v[88:89], v[96:97] op_sel_hi:[1,0]
	s_nop 0
	v_cvt_pk_bf16_f32 v80, v80, v81
	v_cvt_pk_bf16_f32 v81, v82, v83
	v_cvt_pk_bf16_f32 v82, v86, v87
	v_cvt_pk_bf16_f32 v83, v84, v85
	ds_write_b128 v203, v[80:83]
	ds_read_b128 v[232:235], v205
	v_lshl_add_u64 v[248:249], v[98:99], 0, v[250:251]
	s_waitcnt lgkmcnt(2)
	global_store_dwordx4 v[246:247], v[228:231], off
	s_nop 1
	v_ffbh_u32_e32 v80, v153
	v_min_u32_e32 v83, 32, v80
	v_lshlrev_b64 v[80:81], v83, v[152:153]
	v_min_u32_e32 v80, 1, v80
	v_or_b32_e32 v80, v81, v80
	v_cvt_f32_u32_e32 v80, v80
	v_sub_u32_e32 v81, 32, v83
	v_or_b32_e32 v82, 48, v140
	v_mad_i64_i32 v[82:83], s[2:3], v82, s86, v[142:143]
	v_ldexp_f32 v80, v80, v81
	v_fmamk_f32 v80, v80, 0x2e800000, v236
	v_cmp_gt_f32_e32 vcc, s20, v80
	v_mul_f32_e32 v81, 0x4b800000, v80
	v_lshl_add_u64 v[82:83], v[82:83], 0, v[144:145]
	v_cndmask_b32_e32 v80, v80, v81, vcc
	v_rsq_f32_e32 v80, v80
	s_nop 0
	v_mul_f32_e32 v81, 0x45800000, v80
	v_cndmask_b32_e32 v80, v80, v81, vcc
	v_pk_mul_f32 v[50:51], v[50:51], v[80:81] op_sel_hi:[1,0]
	v_pk_mul_f32 v[48:49], v[48:49], v[80:81] op_sel_hi:[1,0]
	v_pk_mul_f32 v[58:59], v[58:59], v[80:81] op_sel_hi:[1,0]
	v_pk_mul_f32 v[56:57], v[56:57], v[80:81] op_sel_hi:[1,0]
	v_cvt_pk_bf16_f32 v48, v48, v49
	v_cvt_pk_bf16_f32 v49, v50, v51
	v_cvt_pk_bf16_f32 v50, v56, v57
	v_cvt_pk_bf16_f32 v51, v58, v59
	ds_write_b128 v202, v[48:51]
	ds_read_b128 v[228:231], v204
	v_lshl_add_u64 v[246:247], v[82:83], 0, v[250:251]
	s_waitcnt lgkmcnt(2)
	global_store_dwordx4 v[248:249], v[232:235], off offset:256
	v_pk_mul_f32 v[56:57], v[74:75], v[80:81] op_sel_hi:[1,0]
	v_pk_mul_f32 v[58:59], v[72:73], v[80:81] op_sel_hi:[1,0]
	v_pk_mul_f32 v[50:51], v[66:67], v[80:81] op_sel_hi:[1,0]
	v_pk_mul_f32 v[48:49], v[64:65], v[80:81] op_sel_hi:[1,0]
	s_nop 0
	v_cvt_pk_bf16_f32 v48, v48, v49
	v_cvt_pk_bf16_f32 v49, v50, v51
	v_cvt_pk_bf16_f32 v50, v58, v59
	v_cvt_pk_bf16_f32 v51, v56, v57
	ds_write_b128 v203, v[48:51]
	ds_read_b128 v[232:235], v205
	v_lshl_add_u64 v[248:249], v[82:83], 0, v[250:251]
	s_waitcnt lgkmcnt(2)
	global_store_dwordx4 v[246:247], v[228:231], off
	s_nop 1
	v_ffbh_u32_e32 v48, v151
	v_min_u32_e32 v50, 32, v48
	v_lshlrev_b64 v[48:49], v50, v[150:151]
	v_min_u32_e32 v48, 1, v48
	v_or_b32_e32 v48, v49, v48
	v_cvt_f32_u32_e32 v48, v48
	v_sub_u32_e32 v49, 32, v50
	v_ldexp_f32 v48, v48, v49
	v_fmamk_f32 v48, v48, 0x2e800000, v236
	v_cmp_gt_f32_e32 vcc, s20, v48
	v_mul_f32_e32 v49, 0x4b800000, v48
	s_nop 0
	v_cndmask_b32_e32 v48, v48, v49, vcc
	v_rsq_f32_e32 v48, v48
	s_nop 0
	v_mul_f32_e32 v49, 0x45800000, v48
	v_cndmask_b32_e32 v56, v48, v49, vcc
	v_mad_i64_i32 v[48:49], s[2:3], v141, s86, v[142:143]
	v_lshl_add_u64 v[58:59], v[48:49], 0, v[144:145]
	v_pk_mul_f32 v[50:51], v[54:55], v[56:57] op_sel_hi:[1,0]
	v_pk_mul_f32 v[48:49], v[52:53], v[56:57] op_sel_hi:[1,0]
	v_pk_mul_f32 v[52:53], v[62:63], v[56:57] op_sel_hi:[1,0]
	v_pk_mul_f32 v[54:55], v[60:61], v[56:57] op_sel_hi:[1,0]
	v_cvt_pk_bf16_f32 v48, v48, v49
	v_cvt_pk_bf16_f32 v49, v50, v51
	v_cvt_pk_bf16_f32 v50, v54, v55
	v_cvt_pk_bf16_f32 v51, v52, v53
	ds_write_b128 v202, v[48:51]
	ds_read_b128 v[228:231], v204
	v_lshl_add_u64 v[246:247], v[58:59], 0, v[250:251]
	s_waitcnt lgkmcnt(2)
	global_store_dwordx4 v[248:249], v[232:235], off offset:256
	v_pk_mul_f32 v[52:53], v[78:79], v[56:57] op_sel_hi:[1,0]
	v_pk_mul_f32 v[54:55], v[76:77], v[56:57] op_sel_hi:[1,0]
	v_pk_mul_f32 v[50:51], v[70:71], v[56:57] op_sel_hi:[1,0]
	v_pk_mul_f32 v[48:49], v[68:69], v[56:57] op_sel_hi:[1,0]
	s_nop 0
	v_cvt_pk_bf16_f32 v48, v48, v49
	v_cvt_pk_bf16_f32 v49, v50, v51
	v_cvt_pk_bf16_f32 v50, v54, v55
	v_cvt_pk_bf16_f32 v51, v52, v53
	ds_write_b128 v203, v[48:51]
	ds_read_b128 v[232:235], v205
	v_lshl_add_u64 v[248:249], v[58:59], 0, v[250:251]
	s_waitcnt lgkmcnt(2)
	global_store_dwordx4 v[246:247], v[228:231], off
	s_nop 1
	v_ffbh_u32_e32 v48, v149
	v_min_u32_e32 v51, 32, v48
	v_lshlrev_b64 v[48:49], v51, v[148:149]
	v_min_u32_e32 v48, 1, v48
	v_or_b32_e32 v48, v49, v48
	v_cvt_f32_u32_e32 v48, v48
	v_sub_u32_e32 v49, 32, v51
	v_add_u32_e32 v50, 0x90, v140
	v_mad_i64_i32 v[50:51], s[2:3], v50, s86, v[142:143]
	v_ldexp_f32 v48, v48, v49
	v_fmamk_f32 v48, v48, 0x2e800000, v236
	v_cmp_gt_f32_e32 vcc, s20, v48
	v_mul_f32_e32 v49, 0x4b800000, v48
	v_lshl_add_u64 v[50:51], v[50:51], 0, v[144:145]
	v_cndmask_b32_e32 v48, v48, v49, vcc
	v_rsq_f32_e32 v48, v48
	s_nop 0
	v_mul_f32_e32 v49, 0x45800000, v48
	v_cndmask_b32_e32 v48, v48, v49, vcc
	v_pk_mul_f32 v[34:35], v[34:35], v[48:49] op_sel_hi:[1,0]
	v_pk_mul_f32 v[32:33], v[32:33], v[48:49] op_sel_hi:[1,0]
	v_pk_mul_f32 v[38:39], v[38:39], v[48:49] op_sel_hi:[1,0]
	v_pk_mul_f32 v[36:37], v[36:37], v[48:49] op_sel_hi:[1,0]
	v_cvt_pk_bf16_f32 v32, v32, v33
	v_cvt_pk_bf16_f32 v33, v34, v35
	v_cvt_pk_bf16_f32 v34, v36, v37
	v_cvt_pk_bf16_f32 v35, v38, v39
	ds_write_b128 v202, v[32:35]
	ds_read_b128 v[228:231], v204
	v_lshl_add_u64 v[246:247], v[50:51], 0, v[250:251]
	s_waitcnt lgkmcnt(2)
	global_store_dwordx4 v[248:249], v[232:235], off offset:256
	v_pk_mul_f32 v[36:37], v[46:47], v[48:49] op_sel_hi:[1,0]
	v_pk_mul_f32 v[38:39], v[44:45], v[48:49] op_sel_hi:[1,0]
	v_pk_mul_f32 v[34:35], v[42:43], v[48:49] op_sel_hi:[1,0]
	v_pk_mul_f32 v[32:33], v[40:41], v[48:49] op_sel_hi:[1,0]
	s_nop 0
	v_cvt_pk_bf16_f32 v32, v32, v33
	v_cvt_pk_bf16_f32 v33, v34, v35
	v_cvt_pk_bf16_f32 v34, v38, v39
	v_cvt_pk_bf16_f32 v35, v36, v37
	ds_write_b128 v203, v[32:35]
	ds_read_b128 v[232:235], v205
	v_lshl_add_u64 v[248:249], v[50:51], 0, v[250:251]
	s_waitcnt lgkmcnt(2)
	global_store_dwordx4 v[246:247], v[228:231], off
	s_nop 1
	v_ffbh_u32_e32 v32, v147
	v_min_u32_e32 v35, 32, v32
	v_lshlrev_b64 v[32:33], v35, v[146:147]
	v_min_u32_e32 v32, 1, v32
	v_or_b32_e32 v32, v33, v32
	v_cvt_f32_u32_e32 v32, v32
	v_sub_u32_e32 v33, 32, v35
	v_add_u32_e32 v34, 0xa0, v140
	v_mad_i64_i32 v[34:35], s[2:3], v34, s86, v[142:143]
	v_ldexp_f32 v32, v32, v33
	v_fmamk_f32 v32, v32, 0x2e800000, v236
	v_cmp_gt_f32_e32 vcc, s20, v32
	v_mul_f32_e32 v33, 0x4b800000, v32
	v_lshl_add_u64 v[34:35], v[34:35], 0, v[144:145]
	v_cndmask_b32_e32 v32, v32, v33, vcc
	v_rsq_f32_e32 v32, v32
	s_nop 0
	v_mul_f32_e32 v33, 0x45800000, v32
	v_cndmask_b32_e32 v32, v32, v33, vcc
	v_pk_mul_f32 v[18:19], v[18:19], v[32:33] op_sel_hi:[1,0]
	v_pk_mul_f32 v[16:17], v[16:17], v[32:33] op_sel_hi:[1,0]
	v_pk_mul_f32 v[22:23], v[22:23], v[32:33] op_sel_hi:[1,0]
	v_pk_mul_f32 v[20:21], v[20:21], v[32:33] op_sel_hi:[1,0]
	v_cvt_pk_bf16_f32 v16, v16, v17
	v_cvt_pk_bf16_f32 v17, v18, v19
	v_cvt_pk_bf16_f32 v18, v20, v21
	v_cvt_pk_bf16_f32 v19, v22, v23
	ds_write_b128 v202, v[16:19]
	ds_read_b128 v[228:231], v204
	v_lshl_add_u64 v[246:247], v[34:35], 0, v[250:251]
	s_waitcnt lgkmcnt(2)
	global_store_dwordx4 v[248:249], v[232:235], off offset:256
	v_pk_mul_f32 v[20:21], v[30:31], v[32:33] op_sel_hi:[1,0]
	v_pk_mul_f32 v[22:23], v[28:29], v[32:33] op_sel_hi:[1,0]
	v_pk_mul_f32 v[18:19], v[26:27], v[32:33] op_sel_hi:[1,0]
	v_pk_mul_f32 v[16:17], v[24:25], v[32:33] op_sel_hi:[1,0]
	s_nop 0
	v_cvt_pk_bf16_f32 v16, v16, v17
	v_cvt_pk_bf16_f32 v17, v18, v19
	v_cvt_pk_bf16_f32 v18, v22, v23
	v_cvt_pk_bf16_f32 v19, v20, v21
	ds_write_b128 v203, v[16:19]
	ds_read_b128 v[232:235], v205
	v_lshl_add_u64 v[248:249], v[34:35], 0, v[250:251]
	s_waitcnt lgkmcnt(2)
	global_store_dwordx4 v[246:247], v[228:231], off
	s_nop 1
	v_ffbh_u32_e32 v16, v139
	v_min_u32_e32 v19, 32, v16
	v_lshlrev_b64 v[16:17], v19, v[138:139]
	v_min_u32_e32 v16, 1, v16
	v_or_b32_e32 v16, v17, v16
	v_cvt_f32_u32_e32 v16, v16
	v_sub_u32_e32 v17, 32, v19
	v_add_u32_e32 v18, 0xb0, v140
	v_mad_i64_i32 v[18:19], s[2:3], v18, s86, v[142:143]
	v_ldexp_f32 v16, v16, v17
	v_fmamk_f32 v16, v16, 0x2e800000, v236
	v_cmp_gt_f32_e32 vcc, s20, v16
	v_mul_f32_e32 v17, 0x4b800000, v16
	v_lshl_add_u64 v[18:19], v[18:19], 0, v[144:145]
	v_cndmask_b32_e32 v16, v16, v17, vcc
	v_rsq_f32_e32 v16, v16
	s_mov_b64 s[2:3], -1
	v_mul_f32_e32 v17, 0x45800000, v16
	v_cndmask_b32_e32 v16, v16, v17, vcc
	v_pk_mul_f32 v[2:3], v[2:3], v[16:17] op_sel_hi:[1,0]
	v_pk_mul_f32 v[0:1], v[0:1], v[16:17] op_sel_hi:[1,0]
	v_pk_mul_f32 v[6:7], v[6:7], v[16:17] op_sel_hi:[1,0]
	v_pk_mul_f32 v[4:5], v[4:5], v[16:17] op_sel_hi:[1,0]
	v_cvt_pk_bf16_f32 v0, v0, v1
	v_cvt_pk_bf16_f32 v1, v2, v3
	v_cvt_pk_bf16_f32 v2, v4, v5
	v_cvt_pk_bf16_f32 v3, v6, v7
	ds_write_b128 v202, v[0:3]
	ds_read_b128 v[228:231], v204
	v_lshl_add_u64 v[246:247], v[18:19], 0, v[250:251]
	s_waitcnt lgkmcnt(2)
	global_store_dwordx4 v[248:249], v[232:235], off offset:256
	v_pk_mul_f32 v[4:5], v[14:15], v[16:17] op_sel_hi:[1,0]
	v_pk_mul_f32 v[6:7], v[12:13], v[16:17] op_sel_hi:[1,0]
	v_pk_mul_f32 v[2:3], v[10:11], v[16:17] op_sel_hi:[1,0]
	v_pk_mul_f32 v[0:1], v[8:9], v[16:17] op_sel_hi:[1,0]
	s_andn2_b64 vcc, exec, s[4:5]
	v_cvt_pk_bf16_f32 v0, v0, v1
	v_cvt_pk_bf16_f32 v1, v2, v3
	v_cvt_pk_bf16_f32 v2, v6, v7
	v_cvt_pk_bf16_f32 v3, v4, v5
	ds_write_b128 v203, v[0:3]
	ds_read_b128 v[232:235], v205
	v_lshl_add_u64 v[248:249], v[18:19], 0, v[250:251]
	s_waitcnt lgkmcnt(2)
	global_store_dwordx4 v[246:247], v[228:231], off
	s_waitcnt lgkmcnt(0)
	global_store_dwordx4 v[248:249], v[232:235], off offset:256
	s_cbranch_vccnz .LBB0_128
	v_mov_b32_e32 v112, v192
	v_mov_b32_e32 v116, v192
	v_mov_b32_e32 v96, v192
	v_mov_b32_e32 v100, v192
	v_mov_b32_e32 v80, v192
	v_mov_b32_e32 v84, v192
	v_mov_b32_e32 v48, v192
	v_mov_b32_e32 v56, v192
	v_mov_b32_e32 v120, v192
	v_mov_b32_e32 v124, v192
	v_mov_b32_e32 v104, v192
	v_mov_b32_e32 v108, v192
	v_mov_b32_e32 v88, v192
	v_mov_b32_e32 v92, v192
	v_mov_b32_e32 v64, v192
	v_mov_b32_e32 v72, v192
	v_mov_b32_e32 v52, v192
	v_mov_b32_e32 v60, v192
	v_mov_b32_e32 v32, v192
	v_mov_b32_e32 v36, v192
	v_mov_b32_e32 v16, v192
	v_mov_b32_e32 v20, v192
	v_mov_b32_e32 v0, v192
	v_mov_b32_e32 v4, v192
	v_mov_b32_e32 v68, v192
	v_mov_b32_e32 v76, v192
	v_mov_b32_e32 v40, v192
	v_mov_b32_e32 v44, v192
	v_mov_b32_e32 v24, v192
	v_mov_b32_e32 v28, v192
	v_mov_b32_e32 v8, v192
	v_mov_b32_e32 v12, v195
	s_nop 0
	v_mov_b32_e32 v113, v112
	v_mov_b32_e32 v114, v112
	v_mov_b32_e32 v115, v112
	v_mov_b32_e32 v117, v116
	v_mov_b32_e32 v118, v116
	v_mov_b32_e32 v119, v116
	v_mov_b32_e32 v97, v96
	v_mov_b32_e32 v98, v96
	v_mov_b32_e32 v99, v96
	v_mov_b32_e32 v101, v100
	v_mov_b32_e32 v102, v100
	v_mov_b32_e32 v103, v100
	v_mov_b32_e32 v81, v80
	v_mov_b32_e32 v82, v80
	v_mov_b32_e32 v83, v80
	v_mov_b32_e32 v85, v84
	v_mov_b32_e32 v86, v84
	v_mov_b32_e32 v87, v84
	s_nop 0
	v_mov_b32_e32 v49, v48
	v_mov_b32_e32 v50, v48
	v_mov_b32_e32 v51, v48
	v_mov_b32_e32 v57, v56
	v_mov_b32_e32 v58, v56
	v_mov_b32_e32 v59, v56
	v_mov_b32_e32 v121, v120
	v_mov_b32_e32 v122, v120
	v_mov_b32_e32 v123, v120
	v_mov_b32_e32 v125, v124
	v_mov_b32_e32 v126, v124
	v_mov_b32_e32 v127, v124
	v_mov_b32_e32 v105, v104
	v_mov_b32_e32 v106, v104
	v_mov_b32_e32 v107, v104
	v_mov_b32_e32 v109, v108
	v_mov_b32_e32 v110, v108
	v_mov_b32_e32 v111, v108
	s_nop 0
	v_mov_b32_e32 v89, v88
	v_mov_b32_e32 v90, v88
	v_mov_b32_e32 v91, v88
	v_mov_b32_e32 v93, v92
	v_mov_b32_e32 v94, v92
	v_mov_b32_e32 v95, v92
	v_mov_b32_e32 v65, v64
	v_mov_b32_e32 v66, v64
	v_mov_b32_e32 v67, v64
	v_mov_b32_e32 v73, v72
	v_mov_b32_e32 v74, v72
	v_mov_b32_e32 v75, v72
	v_mov_b32_e32 v53, v52
	v_mov_b32_e32 v54, v52
	v_mov_b32_e32 v55, v52
	v_mov_b32_e32 v61, v60
	v_mov_b32_e32 v62, v60
	v_mov_b32_e32 v63, v60
	s_nop 0
	v_mov_b32_e32 v33, v32
	v_mov_b32_e32 v34, v32
	v_mov_b32_e32 v35, v32
	v_mov_b32_e32 v37, v36
	v_mov_b32_e32 v38, v36
	v_mov_b32_e32 v39, v36
	v_mov_b32_e32 v17, v16
	v_mov_b32_e32 v18, v16
	v_mov_b32_e32 v19, v16
	v_mov_b32_e32 v21, v20
	v_mov_b32_e32 v22, v20
	v_mov_b32_e32 v23, v20
	v_mov_b32_e32 v1, v0
	v_mov_b32_e32 v2, v0
	v_mov_b32_e32 v3, v0
	v_mov_b32_e32 v5, v4
	v_mov_b32_e32 v6, v4
	v_mov_b32_e32 v7, v4
	s_nop 0
	v_mov_b32_e32 v69, v68
	v_mov_b32_e32 v70, v68
	v_mov_b32_e32 v71, v68
	v_mov_b32_e32 v77, v76
	v_mov_b32_e32 v78, v76
	v_mov_b32_e32 v79, v76
	v_mov_b32_e32 v41, v40
	v_mov_b32_e32 v42, v40
	v_mov_b32_e32 v43, v40
	v_mov_b32_e32 v45, v44
	v_mov_b32_e32 v46, v44
	v_mov_b32_e32 v47, v44
	v_mov_b32_e32 v25, v24
	v_mov_b32_e32 v26, v24
	v_mov_b32_e32 v27, v24
	v_mov_b32_e32 v29, v28
	v_mov_b32_e32 v30, v28
	v_mov_b32_e32 v31, v28
	s_mov_b64 s[2:3], 0
	v_mov_b32_e32 v9, v8
	v_mov_b32_e32 v10, v8
	v_mov_b32_e32 v11, v8
	v_mov_b32_e32 v13, v12
	v_mov_b32_e32 v14, v12
	v_mov_b32_e32 v15, v12
	s_branch .LBB0_128
